# P3: items re-indexed so each XCD owns a contiguous range of (chunk, third) items - conv items of neighbouring chunks (which re-read each other's rows) share an L2
# speedup vs baseline: 1.0048x; 1.0009x over previous
; #define LAS __attribute__((address_space(3)))
; __device__ __forceinline__ unsigned f2bf(float f) { return pk2(f, 0.f) & 0xffffu; }
; __device__ __forceinline__ void gate_stash(LAS unsigned char* lds, const float* wg_f, const float* wg_b) {
;     ...
;         {
;             const int d = wave >> 2, lr_g = lane & 15, lq_g = lane >> 4; const float* wg = d ? wg_b : wg_f;
; #pragma unroll
;             for (int c4 = 0; c4 < 4; ++c4) { const int colc = 16 * (4 * (wave & 3) + c4) + lr_g; bf16x8 b1, b2;
; #pragma unroll
;                 for (int e = 0; e < 8; ++e) { const float wv = wg[(((8 * lq_g) & 15) + e) * 256 + colc]; const unsigned hi = f2bf(wv); const float rem = wv - __builtin_bit_cast(float, hi << 16);
;                     b1[e] = (short)hi; b2[e] = (lq_g < 2) ? (short)f2bf(rem) : (short)0; }
;                 *(LAS bf16x8*)(lds + 65536 + ((wave * 8 + c4 * 2) * 64 + lane) * 16) = b1; *(LAS bf16x8*)(lds + 65536 + ((wave * 8 + c4 * 2 + 1) * 64 + lane) * 16) = b2; }
.LBB0_379:
	s_add_u32 s20, s78, 0x1000000
	v_mov_b32_e32 v1, v0
	s_addc_u32 s21, s79, 0
	s_mov_b32 s73, 0x5040100
	v_readfirstlane_b32 s0, v1
	s_cmpk_lt_u32 s0, 0x100
	v_lshlrev_b32_e32 v3, 7, v1
	v_and_b32_e32 v2, 15, v1
	s_cselect_b32 s5, s63, s67
	s_cselect_b32 s4, s62, s66
	s_and_b32 s1, s0, 0xc0
	v_and_b32_e32 v3, 0x800, v3
	v_or3_b32 v2, s1, v2, v3
	v_lshlrev_b32_e32 v2, 2, v2
	v_or_b32_e32 v7, 0x1000, v2
	v_or_b32_e32 v9, 0x1400, v2
	global_load_dword v3, v2, s[4:5]
	global_load_dword v4, v2, s[4:5] offset:1024
	global_load_dword v5, v2, s[4:5] offset:2048
	global_load_dword v6, v2, s[4:5] offset:3072
	global_load_dword v8, v7, s[4:5]
	v_or_b32_e32 v10, 0x1800, v2
	global_load_dword v11, v9, s[4:5]
	global_load_dword v12, v10, s[4:5]
	v_or_b32_e32 v13, 0x1c00, v2
	global_load_dword v14, v13, s[4:5]
	v_or_b32_e32 v17, 0x400, v2
	global_load_dword v18, v17, s[4:5] offset:64
	global_load_dword v15, v2, s[4:5] offset:64
	v_or_b32_e32 v19, 0x800, v2
	v_or_b32_e32 v20, 0xc00, v2
	global_load_dword v21, v10, s[4:5] offset:64
	global_load_dword v22, v13, s[4:5] offset:64
	global_load_dword v23, v19, s[4:5] offset:64
	global_load_dword v24, v20, s[4:5] offset:64
	global_load_dword v25, v17, s[4:5] offset:128
	global_load_dword v26, v2, s[4:5] offset:128
	global_load_dword v27, v2, s[4:5] offset:192
	global_load_dword v28, v7, s[4:5] offset:64
	global_load_dword v29, v9, s[4:5] offset:64
	global_load_dword v30, v7, s[4:5] offset:128
	global_load_dword v31, v9, s[4:5] offset:128
	global_load_dword v32, v9, s[4:5] offset:192
	global_load_dword v33, v7, s[4:5] offset:192
	s_lshl_b32 s0, s0, 7
	s_and_b32 s0, s0, 0xffffe000
	v_and_b32_e32 v1, 63, v1
	s_add_i32 s0, s0, 0
	v_cmp_gt_u32_e32 vcc, 32, v1
	v_lshl_add_u32 v16, v1, 4, s0
	v_add_u32_e32 v16, 0x10000, v16
	v_writelane_b32 v240, s12, 34
	s_movk_i32 s70, 0x100
	s_movk_i32 s71, 0xc0
	v_mov_b32_e32 v151, 0
	s_movk_i32 s72, 0x1000
	s_cmpk_gt_i32 s2, 0x34f
	v_writelane_b32 v240, s13, 35
	s_waitcnt vmcnt(22)
	v_cvt_pk_bf16_f32 v2, v3, 0
	v_lshlrev_b32_e32 v35, 16, v2
	s_waitcnt vmcnt(20)
	v_cvt_pk_bf16_f32 v9, v5, 0
	s_waitcnt vmcnt(19)
	v_cvt_pk_bf16_f32 v34, v6, 0
	v_lshlrev_b32_e32 v37, 16, v9
	v_lshlrev_b32_e32 v38, 16, v34
	s_waitcnt vmcnt(16)
	v_cvt_pk_bf16_f32 v41, v12, 0
	v_cvt_pk_bf16_f32 v39, v8, 0
	v_sub_f32_e32 v5, v5, v37
	v_lshlrev_b32_e32 v37, 16, v41
	v_sub_f32_e32 v3, v3, v35
	v_sub_f32_e32 v6, v6, v38
	v_lshlrev_b32_e32 v35, 16, v39
	v_sub_f32_e32 v12, v12, v37
	global_load_dword v37, v10, s[4:5] offset:128
	global_load_dword v38, v13, s[4:5] offset:128
	s_nop 0
	global_load_dword v13, v13, s[4:5] offset:192
	s_nop 0
	global_load_dword v10, v10, s[4:5] offset:192
	v_cvt_pk_bf16_f32 v3, v3, s0
	global_load_dword v43, v19, s[4:5] offset:128
	v_sub_f32_e32 v8, v8, v35
	v_cndmask_b32_e32 v1, 0, v3, vcc
	v_cvt_pk_bf16_f32 v3, v8, s0
	v_cndmask_b32_e32 v8, 0, v3, vcc
	v_perm_b32 v3, v34, v9, s73
	global_load_dword v34, v20, s[4:5] offset:128
	v_cvt_pk_bf16_f32 v7, v4, 0
	v_lshlrev_b32_e32 v36, 16, v7
	v_cvt_pk_bf16_f32 v40, v11, 0
	s_waitcnt vmcnt(21)
	v_cvt_pk_bf16_f32 v42, v14, 0
	v_sub_f32_e32 v4, v4, v36
	v_lshlrev_b32_e32 v36, 16, v40
	v_perm_b32 v2, v7, v2, s73
	v_lshlrev_b32_e32 v7, 16, v42
	v_cvt_pk_bf16_f32 v4, v4, s0
	v_cvt_pk_bf16_f32 v5, v5, s0
	v_cvt_pk_bf16_f32 v6, v6, s0
	v_sub_f32_e32 v11, v11, v36
	v_sub_f32_e32 v7, v14, v7
	v_cndmask_b32_e32 v35, 0, v4, vcc
	v_cndmask_b32_e32 v36, 0, v5, vcc
	v_cndmask_b32_e32 v6, 0, v6, vcc
	v_cvt_pk_bf16_f32 v4, v11, s0
	v_cvt_pk_bf16_f32 v5, v12, s0
	v_cvt_pk_bf16_f32 v7, v7, s0
	v_cndmask_b32_e32 v11, 0, v4, vcc
	v_cndmask_b32_e32 v12, 0, v5, vcc
	v_perm_b32 v5, v42, v41, s73
	v_perm_b32 v4, v40, v39, s73
	v_cndmask_b32_e32 v9, 0, v7, vcc
	v_perm_b32 v7, v6, v36, s73
	v_perm_b32 v6, v35, v1, s73
	s_waitcnt vmcnt(19)
	v_cvt_pk_bf16_f32 v1, v15, 0
	v_perm_b32 v9, v9, v12, s73
	v_perm_b32 v8, v11, v8, s73
	ds_write_b128 v16, v[2:5]
	ds_write_b128 v16, v[6:9] offset:1024
	v_lshlrev_b32_e32 v2, 16, v1
	v_sub_f32_e32 v2, v15, v2
	global_load_dword v12, v20, s[4:5] offset:192
	global_load_dword v14, v19, s[4:5] offset:192
	global_load_dword v15, v17, s[4:5] offset:192
	v_cvt_pk_bf16_f32 v2, v2, s0
	v_cndmask_b32_e32 v6, 0, v2, vcc
	v_cvt_pk_bf16_f32 v2, v18, 0
	v_lshlrev_b32_e32 v3, 16, v2
	v_sub_f32_e32 v3, v18, v3
	v_cvt_pk_bf16_f32 v3, v3, s0
	v_cndmask_b32_e32 v11, 0, v3, vcc
	s_waitcnt vmcnt(19)
	v_cvt_pk_bf16_f32 v3, v23, 0
	v_lshlrev_b32_e32 v4, 16, v3
	v_sub_f32_e32 v4, v23, v4
	v_cvt_pk_bf16_f32 v4, v4, s0
	s_waitcnt vmcnt(18)
; #define LAS __attribute__((address_space(3)))
; __device__ __forceinline__ unsigned f2bf(float f) { return pk2(f, 0.f) & 0xffffu; }
; __device__ __forceinline__ void gate_stash(LAS unsigned char* lds, const float* wg_f, const float* wg_b) {
;     ...
;                 for (int e = 0; e < 8; ++e) { const float wv = wg[(((8 * lq_g) & 15) + e) * 256 + colc]; const unsigned hi = f2bf(wv); const float rem = wv - __builtin_bit_cast(float, hi << 16);
;                     b1[e] = (short)hi; b2[e] = (lq_g < 2) ? (short)f2bf(rem) : (short)0; }
;                 *(LAS bf16x8*)(lds + 65536 + ((wave * 8 + c4 * 2) * 64 + lane) * 16) = b1; *(LAS bf16x8*)(lds + 65536 + ((wave * 8 + c4 * 2 + 1) * 64 + lane) * 16) = b2; }
; __global__ void __launch_bounds__(NT, 2) fwd_kernel(Args args) {
;     ...
;         for (int it = bl; it < 816 + 32; it += GRID) {
;             PHASE_IDS
;             if (it < 816) {
;                 const int ch = it / 3, third = it % 3, ch0 = third * 256 + 8 * (tid & 31), t0 = 4 * (tid >> 5);
	v_cvt_pk_bf16_f32 v8, v24, 0
	v_cndmask_b32_e32 v7, 0, v4, vcc
	v_lshlrev_b32_e32 v4, 16, v8
	v_sub_f32_e32 v4, v24, v4
	v_cvt_pk_bf16_f32 v4, v4, s0
	v_cndmask_b32_e32 v17, 0, v4, vcc
	s_waitcnt vmcnt(14)
	v_cvt_pk_bf16_f32 v4, v28, 0
	v_lshlrev_b32_e32 v5, 16, v4
	v_sub_f32_e32 v5, v28, v5
	v_cvt_pk_bf16_f32 v5, v5, s0
	s_waitcnt vmcnt(13)
	v_cvt_pk_bf16_f32 v9, v29, 0
	v_cndmask_b32_e32 v18, 0, v5, vcc
	v_lshlrev_b32_e32 v5, 16, v9
	v_sub_f32_e32 v5, v29, v5
	v_cvt_pk_bf16_f32 v5, v5, s0
	v_cndmask_b32_e32 v19, 0, v5, vcc
	v_cvt_pk_bf16_f32 v5, v21, 0
	v_lshlrev_b32_e32 v20, 16, v5
	v_sub_f32_e32 v20, v21, v20
	v_cvt_pk_bf16_f32 v21, v22, 0
	v_perm_b32 v2, v2, v1, s73
	v_lshlrev_b32_e32 v1, 16, v21
	v_sub_f32_e32 v1, v22, v1
	v_cvt_pk_bf16_f32 v20, v20, s0
	v_cvt_pk_bf16_f32 v1, v1, s0
	v_cndmask_b32_e32 v20, 0, v20, vcc
	v_cndmask_b32_e32 v1, 0, v1, vcc
	v_perm_b32 v5, v21, v5, s73
	v_perm_b32 v4, v9, v4, s73
	v_perm_b32 v3, v8, v3, s73
	v_perm_b32 v9, v1, v20, s73
	v_cvt_pk_bf16_f32 v1, v26, 0
	v_perm_b32 v8, v19, v18, s73
	v_perm_b32 v7, v17, v7, s73
	v_perm_b32 v6, v11, v6, s73
	ds_write_b128 v16, v[2:5] offset:2048
	ds_write_b128 v16, v[6:9] offset:3072
	v_lshlrev_b32_e32 v2, 16, v1
	v_sub_f32_e32 v2, v26, v2
	v_cvt_pk_bf16_f32 v2, v2, s0
	v_cndmask_b32_e32 v6, 0, v2, vcc
	v_cvt_pk_bf16_f32 v2, v25, 0
	v_lshlrev_b32_e32 v3, 16, v2
	v_sub_f32_e32 v3, v25, v3
	v_cvt_pk_bf16_f32 v3, v3, s0
	v_cndmask_b32_e32 v11, 0, v3, vcc
	s_waitcnt vmcnt(4)
	v_cvt_pk_bf16_f32 v3, v43, 0
	v_lshlrev_b32_e32 v4, 16, v3
	v_sub_f32_e32 v4, v43, v4
	v_cvt_pk_bf16_f32 v4, v4, s0
	s_waitcnt vmcnt(3)
	v_cvt_pk_bf16_f32 v8, v34, 0
	v_cndmask_b32_e32 v7, 0, v4, vcc
	v_lshlrev_b32_e32 v4, 16, v8
	v_sub_f32_e32 v4, v34, v4
	v_cvt_pk_bf16_f32 v4, v4, s0
	v_cndmask_b32_e32 v17, 0, v4, vcc
	v_cvt_pk_bf16_f32 v4, v30, 0
	v_lshlrev_b32_e32 v5, 16, v4
	v_sub_f32_e32 v5, v30, v5
	v_cvt_pk_bf16_f32 v5, v5, s0
	v_cvt_pk_bf16_f32 v9, v31, 0
	v_cndmask_b32_e32 v18, 0, v5, vcc
	v_lshlrev_b32_e32 v5, 16, v9
	v_sub_f32_e32 v5, v31, v5
	v_cvt_pk_bf16_f32 v5, v5, s0
	v_cndmask_b32_e32 v19, 0, v5, vcc
	v_cvt_pk_bf16_f32 v5, v37, 0
	v_cvt_pk_bf16_f32 v21, v38, 0
	v_lshlrev_b32_e32 v20, 16, v5
	v_perm_b32 v2, v2, v1, s73
	v_lshlrev_b32_e32 v1, 16, v21
	v_sub_f32_e32 v20, v37, v20
	v_sub_f32_e32 v1, v38, v1
	v_cvt_pk_bf16_f32 v20, v20, s0
	v_cvt_pk_bf16_f32 v1, v1, s0
	v_cndmask_b32_e32 v20, 0, v20, vcc
	v_cndmask_b32_e32 v1, 0, v1, vcc
	v_perm_b32 v5, v21, v5, s73
	v_perm_b32 v4, v9, v4, s73
	v_perm_b32 v3, v8, v3, s73
	v_perm_b32 v9, v1, v20, s73
	v_cvt_pk_bf16_f32 v1, v27, 0
	v_perm_b32 v8, v19, v18, s73
	v_perm_b32 v7, v17, v7, s73
	v_perm_b32 v6, v11, v6, s73
	ds_write_b128 v16, v[2:5] offset:4096
	ds_write_b128 v16, v[6:9] offset:5120
	v_lshlrev_b32_e32 v2, 16, v1
	v_sub_f32_e32 v2, v27, v2
	v_cvt_pk_bf16_f32 v2, v2, s0
	v_cndmask_b32_e32 v6, 0, v2, vcc
	s_waitcnt vmcnt(0)
	v_cvt_pk_bf16_f32 v2, v15, 0
	v_lshlrev_b32_e32 v3, 16, v2
	v_sub_f32_e32 v3, v15, v3
	v_cvt_pk_bf16_f32 v3, v3, s0
	v_cndmask_b32_e32 v11, 0, v3, vcc
	v_cvt_pk_bf16_f32 v3, v14, 0
	v_lshlrev_b32_e32 v4, 16, v3
	v_sub_f32_e32 v4, v14, v4
	v_cvt_pk_bf16_f32 v4, v4, s0
	v_cvt_pk_bf16_f32 v8, v12, 0
	v_cndmask_b32_e32 v7, 0, v4, vcc
	v_lshlrev_b32_e32 v4, 16, v8
	v_sub_f32_e32 v4, v12, v4
	v_cvt_pk_bf16_f32 v4, v4, s0
	v_cndmask_b32_e32 v12, 0, v4, vcc
	v_cvt_pk_bf16_f32 v4, v33, 0
	v_lshlrev_b32_e32 v5, 16, v4
	v_sub_f32_e32 v5, v33, v5
	v_cvt_pk_bf16_f32 v5, v5, s0
	v_cvt_pk_bf16_f32 v9, v32, 0
	v_cndmask_b32_e32 v14, 0, v5, vcc
	v_lshlrev_b32_e32 v5, 16, v9
	v_sub_f32_e32 v5, v32, v5
	v_cvt_pk_bf16_f32 v5, v5, s0
	v_cndmask_b32_e32 v15, 0, v5, vcc
	v_cvt_pk_bf16_f32 v5, v10, 0
	v_lshlrev_b32_e32 v17, 16, v5
	v_sub_f32_e32 v10, v10, v17
	v_cvt_pk_bf16_f32 v17, v13, 0
	v_lshlrev_b32_e32 v18, 16, v17
	v_sub_f32_e32 v13, v13, v18
	v_cvt_pk_bf16_f32 v10, v10, s0
	v_cvt_pk_bf16_f32 v13, v13, s0
	v_cndmask_b32_e32 v10, 0, v10, vcc
	v_cndmask_b32_e32 v13, 0, v13, vcc
	v_perm_b32 v5, v17, v5, s73
	v_perm_b32 v4, v9, v4, s73
	v_perm_b32 v3, v8, v3, s73
	v_perm_b32 v2, v2, v1, s73
	v_perm_b32 v9, v13, v10, s73
	v_perm_b32 v8, v15, v14, s73
	v_perm_b32 v7, v12, v7, s73
	v_perm_b32 v6, v11, v6, s73
	ds_write_b128 v16, v[2:5] offset:6144
	ds_write_b128 v16, v[6:9] offset:7168
	s_cbranch_scc1 .LBB0_502
	s_and_b32 s97, s2, 7
	s_mul_i32 s97, s97, 0x6a
	s_lshr_b32 s98, s2, 3
	s_add_i32 s97, s97, s98
	s_lshl_b32 s0, s97, 5
	s_lshl_b32 s74, s97, 8
	s_add_i32 s75, s0, 0xffffda00
	s_mov_b32 s92, 0x2aaaaaab
	s_mov_b32 s93, 0xbfb8aa3b
	s_movk_i32 s94, 0x1680
	s_movk_i32 s95, 0x41
	s_movk_i32 s96, 0x600
	v_mov_b32_e32 v1, 0x100
	s_nop 0
	s_branch .LBB0_383

; __global__ void __launch_bounds__(NT, 2) fwd_kernel(Args args) {
;     ...
;         for (int it = bl; it < 816 + 32; it += GRID) {
;             PHASE_IDS
;             if (it < 816) {
;                 const int ch = it / 3, third = it % 3, ch0 = third * 256 + 8 * (tid & 31), t0 = 4 * (tid >> 5);
.LBB0_382:
	s_add_i32 s0, s97, 0x20
	s_add_i32 s74, s74, 0x2000
	s_addk_i32 s75, 0x400
	s_add_i32 s98, s98, 32
	s_cmpk_gt_i32 s98, 0x69
	s_mov_b32 s97, s0
	s_cbranch_scc1 .LBB0_502
